# attention kv-loop back-edge rotation (loop-back barrier becomes the loop head) stacked on the woven attention loop
# speedup vs baseline: 1.0010x; 1.0010x over previous
;     __device__ __forceinline__ static float act(float g, float u) { return g * __builtin_amdgcn_rcpf(1.0f + __builtin_amdgcn_exp2f(g * -1.4426950408889634f)) * u; }
; __device__ __forceinline__ void finishSM(f32x16& p0, f32x16& p1, float alpha, float& l_reg, bf16x8& pa0, bf16x8& pa1, bf16x8& pa2, bf16x8& pa3) {
;     for (int r = 0; r < 16; ++r) p1[r] = __builtin_amdgcn_exp2f(p1[r]);
;     float ps = 0; for (int r = 0; r < 16; ++r) ps += p0[r]; for (int r = 0; r < 16; ++r) ps += p1[r];
;     { auto rr = __builtin_amdgcn_permlane32_swap(__float_as_uint(ps), __float_as_uint(ps), false, false);
;       ps = __uint_as_float(rr[0]) + __uint_as_float(rr[1]); }
;     l_reg = l_reg * alpha + ps;
;     ...
;     PK4(p0, 0, pa0); PK4(p0, 8, pa1); PK4(p1, 0, pa2); PK4(p1, 8, pa3);
;     ...
; }
; template <int KB, bool SK, bool NB = false>
; __device__ __forceinline__ void qkt(f32x16& p0, f32x16& p1, const char* K_lds, int r32, int hi, const bf16x8* qr, bool act, const float* g_lds, float gt) {
;     if (SK && !act) { const float NEG = -__builtin_inff();
; #pragma unroll
;         for (int r = 0; r < 16; ++r) { p0[r] = NEG; p1[r] = NEG; } return; }
;     if constexpr (NB) { p0 = f32x16{}; p1 = f32x16{}; } else
;     { const float* gl = g_lds + KB * 64 + 4 * hi;
; #pragma unroll
;       for (int g4 = 0; g4 < 4; ++g4) { const f32x4 a = *(const f32x4*)(gl + 8 * g4), b = *(const f32x4*)(gl + 32 + 8 * g4);
; #pragma unroll
;         for (int e = 0; e < 4; ++e) { p0[4 * g4 + e] = a[e]; p1[4 * g4 + e] = b[e]; } } }
;     const char* kb[4];
; #pragma unroll
;     for (int dd = 0; dd < 4; ++dd) kb[dd] = K_lds + KB * SHM_K + KSWZ(r32, (dd * 16 + hi * 8) * 2);
; #pragma unroll
;     for (int d0 = 0; d0 < 8; ++d0) { const char* a = kb[d0 & 3] + (d0 >> 2) * 128;
;         bf16x8 b0 = *reinterpret_cast<const bf16x8*>(a);
;         bf16x8 b1 = *reinterpret_cast<const bf16x8*>(a + 32 * 256);
;         p0 = __builtin_amdgcn_mfma_f32_32x32x16_bf16(b0, qr[d0], p0, 0, 0, 0);
;         p1 = __builtin_amdgcn_mfma_f32_32x32x16_bf16(b1, qr[d0], p1, 0, 0, 0); }
; }
; template <int VB, bool SK>
; __device__ __forceinline__ void pv_tile(f32x16* o, int vb0, bf16x8 pa0, bf16x8 pa1, bf16x8 pa2, bf16x8 pa3, bool act) {
;     if (SK && !act) return;
.Lattn_head:
	s_barrier
.LBB0_803:
	v_add_u32_e32 v225, 0x10900, v218
	ds_read_b128 v[64:67], v216 offset:49152
	ds_read_b128 v[84:87], v225
	ds_read_b128 v[88:91], v225 offset:32
	ds_read_b128 v[92:95], v225 offset:64
	ds_read_b128 v[96:99], v225 offset:96
	ds_read_b128 v[100:103], v216 offset:57344
	ds_read_b128 v[104:107], v216 offset:49280
	v_add_f32_e32 v177, 0, v173
	s_waitcnt lgkmcnt(2)
	v_mfma_f32_32x32x16_bf16 v[84:99], v[64:67], v[156:159], v[84:99]
	ds_read_b128 v[68:71], v225 offset:128
	ds_read_b128 v[72:75], v225 offset:160
	ds_read_b128 v[76:79], v225 offset:192
	ds_read_b128 v[80:83], v225 offset:224
	ds_read_b128 v[64:67], v216 offset:57472
	v_add_f32_e32 v177, v175, v177
	v_add_f32_e32 v177, v171, v177
	v_add_f32_e32 v177, v174, v177
	v_add_f32_e32 v177, v170, v177
	v_add_f32_e32 v177, v172, v177
	v_add_f32_e32 v177, v168, v177
	s_waitcnt lgkmcnt(1)
	v_mfma_f32_32x32x16_bf16 v[68:83], v[100:103], v[156:159], v[68:83]
	ds_read_b128 v[100:103], v217 offset:49152
	ds_read_b128 v[108:111], v217 offset:57344
	ds_read_b128 v[178:181], v217 offset:49280
	v_add_f32_e32 v177, v169, v177
	v_add_f32_e32 v177, v163, v177
	v_add_f32_e32 v177, v166, v177
	v_exp_f32_e32 v124, v124
	v_exp_f32_e32 v125, v125
	v_exp_f32_e32 v122, v122
	s_waitcnt lgkmcnt(2)
	v_mfma_f32_32x32x16_bf16 v[84:99], v[100:103], v[152:155], v[84:99]
	ds_read_b128 v[100:103], v217 offset:57472
	ds_read_b128 v[182:185], v220 offset:49152
	ds_read_b128 v[186:189], v220 offset:49280
	ds_read_b128 v[226:229], v220 offset:57344
	ds_read_b128 v[230:233], v220 offset:57472
	ds_read_b128 v[234:237], v221 offset:49152
	ds_read_b128 v[238:241], v221 offset:49280
	v_exp_f32_e32 v123, v123
	v_exp_f32_e32 v118, v118
	v_exp_f32_e32 v119, v119
	v_exp_f32_e32 v114, v114
	v_exp_f32_e32 v115, v115
	v_exp_f32_e32 v112, v112
	s_waitcnt lgkmcnt(8)
	v_mfma_f32_32x32x16_bf16 v[68:83], v[108:111], v[152:155], v[68:83]
	ds_read_b128 v[108:111], v221 offset:57344
	ds_read_b128 v[242:245], v221 offset:57472
	v_exp_f32_e32 v113, v113
	v_exp_f32_e32 v126, v126
	v_exp_f32_e32 v127, v127
	v_exp_f32_e32 v120, v120
	v_exp_f32_e32 v121, v121
	v_exp_f32_e32 v116, v116
	s_waitcnt lgkmcnt(7)
	v_mfma_f32_32x32x16_bf16 v[84:99], v[182:185], v[148:151], v[84:99]
	v_exp_f32_e32 v117, v117
	s_waitcnt lgkmcnt(5)
	v_mfma_f32_32x32x16_bf16 v[68:83], v[226:229], v[148:151], v[68:83]
	s_waitcnt lgkmcnt(3)
	v_mfma_f32_32x32x16_bf16 v[84:99], v[234:237], v[144:147], v[84:99]
	s_waitcnt lgkmcnt(1)
	v_mfma_f32_32x32x16_bf16 v[68:83], v[108:111], v[144:147], v[68:83]
	v_add_f32_e32 v108, v161, v177
	v_add_f32_e32 v108, v164, v108
	v_add_f32_e32 v108, v160, v108
	v_add_f32_e32 v108, v167, v108
	v_add_f32_e32 v108, v162, v108
	v_add_f32_e32 v108, v165, v108
	v_add_f32_e32 v108, v124, v108
	v_mfma_f32_32x32x16_bf16 v[84:99], v[104:107], v[140:143], v[84:99]
	v_add_f32_e32 v104, v125, v108
	v_add_f32_e32 v104, v122, v104
	v_add_f32_e32 v104, v123, v104
	v_add_f32_e32 v104, v118, v104
	v_add_f32_e32 v104, v119, v104
	v_add_f32_e32 v104, v114, v104
	v_add_f32_e32 v104, v115, v104
	v_mfma_f32_32x32x16_bf16 v[68:83], v[64:67], v[140:143], v[68:83]
	v_add_f32_e32 v64, v112, v104
	v_add_f32_e32 v64, v113, v64
	v_add_f32_e32 v64, v126, v64
	v_add_f32_e32 v64, v127, v64
	v_add_f32_e32 v64, v120, v64
	v_add_f32_e32 v64, v121, v64
	v_add_f32_e32 v64, v116, v64
	v_mfma_f32_32x32x16_bf16 v[84:99], v[178:181], v[136:139], v[84:99]
	v_add_f32_e32 v226, v117, v64
	v_mov_b32_e32 v227, v226
	v_cvt_pk_bf16_f32 v64, v173, v175
	v_cvt_pk_bf16_f32 v65, v171, v174
	v_cvt_pk_bf16_f32 v66, v170, v172
	v_cvt_pk_bf16_f32 v67, v168, v169
	s_nop 1
	v_permlane32_swap_b32_e32 v226, v227
	v_mfma_f32_32x32x16_bf16 v[68:83], v[100:103], v[136:139], v[68:83]
	v_cvt_pk_bf16_f32 v100, v163, v166
	v_cvt_pk_bf16_f32 v101, v161, v164
	v_cvt_pk_bf16_f32 v102, v160, v167
	v_cvt_pk_bf16_f32 v103, v162, v165
	v_cvt_pk_bf16_f32 v108, v124, v125
	v_cvt_pk_bf16_f32 v109, v122, v123
	v_cvt_pk_bf16_f32 v110, v118, v119
	v_mfma_f32_32x32x16_bf16 v[84:99], v[186:189], v[132:135], v[84:99]
	v_cvt_pk_bf16_f32 v111, v114, v115
	v_cvt_pk_bf16_f32 v104, v112, v113
	v_cvt_pk_bf16_f32 v105, v126, v127
	v_cvt_pk_bf16_f32 v106, v120, v121
	v_cvt_pk_bf16_f32 v107, v116, v117
	v_permlane32_swap_b32_e32 v64, v66
	v_mfma_f32_32x32x16_bf16 v[68:83], v[230:233], v[132:135], v[68:83]
	v_permlane32_swap_b32_e32 v65, v67
	v_permlane32_swap_b32_e32 v100, v102
	v_permlane32_swap_b32_e32 v101, v103
	v_permlane32_swap_b32_e32 v108, v110
	v_mfma_f32_32x32x16_bf16 v[84:99], v[238:241], v[128:131], v[84:99]
	v_permlane32_swap_b32_e32 v109, v111
	v_permlane32_swap_b32_e32 v104, v106
	v_permlane32_swap_b32_e32 v105, v107
	s_waitcnt lgkmcnt(0)
	v_mfma_f32_32x32x16_bf16 v[68:83], v[242:245], v[128:131], v[68:83]
	ds_read_b64_tr_b16 v[112:113], v213 offset:0
	ds_read_b64_tr_b16 v[114:115], v213 offset:0x800
	ds_read_b64_tr_b16 v[116:117], v213 offset:0x1000
	ds_read_b64_tr_b16 v[118:119], v213 offset:0x1800
	ds_read_b64_tr_b16 v[120:121], v213 offset:0x2000
	ds_read_b64_tr_b16 v[122:123], v213 offset:0x2800
	ds_read_b64_tr_b16 v[124:125], v213 offset:0x3000
	ds_read_b64_tr_b16 v[126:127], v213 offset:0x3800
	s_sub_i32 s46, s14, 64
	s_and_b64 vcc, exec, s[6:7]
	s_ashr_i32 s47, s46, 31
	s_cbranch_vccnz .LBB0_805
	v_lshl_add_u64 v[252:253], s[46:47], 2, v[200:201]
	flat_load_dword v202, v[252:253]
